# ffn2 K-rotation: per-tile k start skewed by (tile&7)*256B to spread L2 channels (v13 + krot sh8)
# speedup vs baseline: 1.0273x; 1.0088x over previous
.LBB0_126:
	s_lshr_b32 s15, s14, 3
	v_mov_b32_e32 v6, v254
	s_and_b32 s16, s15, 0xffffff8
	s_and_b32 s15, s14, 7
	v_ashrrev_i32_e32 v0, 3, v6
	s_lshl_b32 s83, s16, 7
	s_lshl_b32 s14, s14, 4
	v_xor_b32_e32 v5, v0, v6
	s_sub_i32 s14, s14, s83
	v_lshlrev_b32_e32 v1, 3, v5
	s_and_b32 s22, s14, 0xffffff80
	v_and_b32_e32 v7, 56, v1
	v_ashrrev_i32_e32 v1, 31, v0
	s_or_b32 s17, s16, s15
	s_ashr_i32 s23, s22, 31
	v_lshlrev_b64 v[2:3], 12, v[0:1]
	s_lshl_b32 s26, s17, 7
	s_lshl_b64 s[36:37], s[22:23], 13
	s_mov_b64 s[16:17], -1
	s_and_b64 vcc, exec, s[40:41]
	v_lshlrev_b64 v[2:3], 1, v[2:3]
	v_lshlrev_b32_e32 v148, 1, v7
	v_lshlrev_b32_e32 v7, 4, v6
	s_cbranch_vccz .LBB0_128
	s_lshl_b64 s[16:17], s[26:27], 13
	s_add_u32 s16, s25, s16
	s_addc_u32 s17, s33, s17
	s_lshl_b32 s14, s26, 1
	s_and_b32 s14, s14, 0x700
	s_add_u32 s16, s16, s14
	s_addc_u32 s17, s17, 0
	v_lshlrev_b32_e32 v85, 4, v6
	s_add_u32 s40, s44, s36
	v_lshl_add_u64 v[8:9], s[16:17], 0, v[2:3]
	v_readfirstlane_b32 s14, v85
	v_add_u32_e32 v14, 0x1000, v85
	s_addc_u32 s41, s45, s37
	s_lshl_b32 s84, s26, 1
	s_and_b32 s84, s84, 0x700
	s_add_u32 s40, s40, s84
	s_addc_u32 s41, s41, 0
	v_lshl_add_u64 v[8:9], v[8:9], 0, v[148:149]
	s_mov_b32 m0, s14
	s_mov_b64 s[16:17], 0x40000
	v_readfirstlane_b32 s14, v14
	v_add_u32_e32 v14, 0x2000, v85
	v_lshl_add_u64 v[10:11], s[40:41], 0, v[2:3]
	s_barrier
	global_load_lds_dwordx4 v[8:9], off
	v_lshl_add_u64 v[12:13], v[8:9], 0, s[16:17]
	s_mov_b32 m0, s14
	s_mov_b64 s[40:41], 0x80000
	v_readfirstlane_b32 s14, v14
	global_load_lds_dwordx4 v[12:13], off
	v_lshl_add_u64 v[12:13], v[8:9], 0, s[40:41]
	s_mov_b32 m0, s14
	s_mov_b64 s[84:85], 0xc0000
	global_load_lds_dwordx4 v[12:13], off
	v_add_u32_e32 v12, 0x3000, v85
	v_lshl_add_u64 v[8:9], v[8:9], 0, s[84:85]
	v_readfirstlane_b32 s14, v12
	s_mov_b32 m0, s14
	v_add_u32_e32 v12, 0x5000, v85
	global_load_lds_dwordx4 v[8:9], off
	v_add_u32_e32 v8, 0x4000, v85
	v_lshl_add_u64 v[10:11], v[10:11], 0, v[148:149]
	v_readfirstlane_b32 s14, v8
	s_mov_b32 m0, s14
	v_readfirstlane_b32 s14, v12
	v_add_u32_e32 v12, 0x6000, v85
	global_load_lds_dwordx4 v[10:11], off
	v_lshl_add_u64 v[8:9], v[10:11], 0, s[16:17]
	s_mov_b32 m0, s14
	v_readfirstlane_b32 s14, v12
	global_load_lds_dwordx4 v[8:9], off
	v_lshl_add_u64 v[8:9], v[10:11], 0, s[40:41]
	s_mov_b32 m0, s14
	s_mov_b64 s[16:17], 0
	global_load_lds_dwordx4 v[8:9], off
	v_lshl_add_u64 v[8:9], v[10:11], 0, s[84:85]
	v_add_u32_e32 v10, 0x7000, v85
	s_nop 0
	v_readfirstlane_b32 s14, v10
	s_mov_b32 m0, s14
	s_nop 0
	global_load_lds_dwordx4 v[8:9], off

.LBB0_130:
	s_add_u32 s14, s25, s30
	v_cmp_lt_i32_e32 vcc, -1, v4
	s_addc_u32 s17, s33, s31
	s_and_b64 s[30:31], vcc, exec
	v_lshrrev_b32_e32 v7, 4, v6
	v_and_b32_e32 v9, 7, v6
	s_cselect_b32 s31, s17, 0
	s_cselect_b32 s30, s14, 0
	s_add_u32 s28, s44, s28
	v_bfe_u32 v8, v6, 4, 2
	v_bitop3_b32 v7, v7, v9, 3 bitop3:0x6c
	s_addc_u32 s29, s45, s29
	v_lshlrev_b32_e32 v86, 4, v7
	v_bitop3_b32 v7, v8, v9, 4 bitop3:0x36
	v_and_b32_e32 v4, 15, v6
	v_lshlrev_b32_e32 v87, 4, v7
	v_lshrrev_b32_e32 v7, 1, v6
	s_cmp_lg_u64 s[30:31], 0
	v_and_or_b32 v4, v7, s47, v4
	v_lshl_add_u64 v[8:9], s[30:31], 0, v[148:149]
	s_cselect_b64 s[30:31], -1, 0
	s_lshl_b32 s14, s15, 7
	v_lshlrev_b32_e32 v88, 7, v4
	v_lshlrev_b32_e32 v4, 7, v6
	s_add_i32 s14, s83, s14
	s_mov_b32 s15, s27
	v_and_b32_e32 v89, 0x2780, v4
	v_lshl_add_u64 v[6:7], s[28:29], 0, v[148:149]
	v_lshlrev_b64 v[0:1], 13, v[0:1]
	v_lshlrev_b32_e32 v4, 4, v5
	s_lshl_b64 s[14:15], s[14:15], 13
	v_lshl_add_u64 v[64:65], v[8:9], 0, v[2:3]
	v_lshl_add_u64 v[66:67], v[6:7], 0, v[2:3]
	s_and_b32 s16, s56, 7
	s_lshl_b32 s16, s16, 8
	v_mov_b32_e32 v10, s16
	v_mov_b32_e32 v11, 0
	v_lshl_add_u64 v[64:65], v[64:65], 0, v[10:11]
	v_lshl_add_u64 v[66:67], v[66:67], 0, v[10:11]
	v_lshl_add_u64 v[2:3], v[0:1], 0, s[36:37]
	v_and_b32_e32 v148, 0x70, v4
	v_lshl_add_u64 v[0:1], v[0:1], 0, s[14:15]
	s_mov_b64 s[40:41], 0x40000
	s_mov_b64 s[84:85], 0x80000
	s_mov_b64 s[86:87], 0xc0000
	v_lshl_add_u64 v[2:3], v[2:3], 0, v[148:149]
	v_or_b32_e32 v0, v0, v148
	v_mov_b32_e32 v56, 0
	s_mov_b32 s16, 0
	s_mov_b64 s[28:29], 0
	v_lshl_add_u64 v[68:69], v[64:65], 0, s[40:41]
	v_lshl_add_u64 v[70:71], v[64:65], 0, s[84:85]
	v_lshl_add_u64 v[72:73], v[64:65], 0, s[86:87]
	v_lshl_add_u64 v[74:75], v[66:67], 0, s[40:41]
	v_lshl_add_u64 v[76:77], v[66:67], 0, s[84:85]
	v_lshl_add_u64 v[78:79], v[66:67], 0, s[86:87]
	v_lshl_add_u64 v[80:81], s[10:11], 0, v[2:3]
	v_lshl_add_u64 v[82:83], s[10:11], 0, v[0:1]
	s_mov_b32 s17, 0
	v_mov_b32_e32 v57, v56
	v_mov_b32_e32 v58, v56
	v_mov_b32_e32 v59, v56
	v_mov_b32_e32 v0, v56
	v_mov_b32_e32 v1, v56
	v_mov_b32_e32 v2, v56
	v_mov_b32_e32 v3, v56
	v_mov_b32_e32 v4, v56
	v_mov_b32_e32 v5, v56
	v_mov_b32_e32 v6, v56
	v_mov_b32_e32 v7, v56
	v_mov_b32_e32 v8, v56
	v_mov_b32_e32 v9, v56
	v_mov_b32_e32 v10, v56
	v_mov_b32_e32 v11, v56
	v_mov_b32_e32 v12, v56
	v_mov_b32_e32 v13, v56
	v_mov_b32_e32 v14, v56
	v_mov_b32_e32 v15, v56
	v_mov_b32_e32 v16, v56
	v_mov_b32_e32 v17, v56
	v_mov_b32_e32 v18, v56
	v_mov_b32_e32 v19, v56
	v_mov_b32_e32 v20, v56
	v_mov_b32_e32 v21, v56
	v_mov_b32_e32 v22, v56
	v_mov_b32_e32 v23, v56
	v_mov_b32_e32 v24, v56
	v_mov_b32_e32 v25, v56
	v_mov_b32_e32 v26, v56
	v_mov_b32_e32 v27, v56
	v_mov_b32_e32 v28, v56
	v_mov_b32_e32 v29, v56
	v_mov_b32_e32 v30, v56
	v_mov_b32_e32 v31, v56
	v_mov_b32_e32 v32, v56
	v_mov_b32_e32 v33, v56
	v_mov_b32_e32 v34, v56
	v_mov_b32_e32 v35, v56
	v_mov_b32_e32 v36, v56
	v_mov_b32_e32 v37, v56
	v_mov_b32_e32 v38, v56
	v_mov_b32_e32 v39, v56
	s_waitcnt vmcnt(0)
	v_mov_b32_e32 v40, v56
	v_mov_b32_e32 v41, v56
	v_mov_b32_e32 v42, v56
	v_mov_b32_e32 v43, v56
	v_mov_b32_e32 v44, v56
	v_mov_b32_e32 v45, v56
	v_mov_b32_e32 v46, v56
	v_mov_b32_e32 v47, v56
	v_mov_b32_e32 v48, v56
	v_mov_b32_e32 v49, v56
	v_mov_b32_e32 v50, v56
	v_mov_b32_e32 v51, v56
	v_mov_b32_e32 v52, v56
	v_mov_b32_e32 v53, v56
	v_mov_b32_e32 v54, v56
	v_mov_b32_e32 v55, v56
	v_mov_b32_e32 v60, v56
	v_mov_b32_e32 v61, v56
	v_mov_b32_e32 v62, v56
	v_mov_b32_e32 v63, v56
	s_branch .LBB0_132

.LBB0_136:
	s_andn2_b64 vcc, exec, s[14:15]
	s_cbranch_vccnz .LBB0_131
	s_add_i32 s14, s16, 0x8000
	s_and_b32 s14, s14, 0x8000
	v_add_u32_e32 v94, s14, v85
	s_lshl_b32 s15, s26, 1
	s_and_b32 s15, s15, 0x700
	v_readfirstlane_b32 s14, v94
	s_mov_b32 m0, s14
	s_add_u32 s14, s15, s28
	s_add_u32 s14, s14, 0x80
	s_and_b32 s14, s14, 0x1fff
	s_add_u32 s14, s14, 0x1201000
	s_mov_b32 s15, 0
	v_lshl_add_u64 v[92:93], v[82:83], 0, s[14:15]
	s_sub_u32 s14, s14, 0x800000
	v_lshl_add_u64 v[90:91], v[80:81], 0, s[14:15]
	global_load_lds_dwordx4 v[92:93], off
	s_add_u32 m0, m0, 0x1000
	v_lshl_add_u64 v[92:93], v[92:93], 0, s[40:41]
	global_load_lds_dwordx4 v[92:93], off
	s_add_u32 m0, m0, 0x1000
	v_lshl_add_u64 v[92:93], v[92:93], 0, s[40:41]
	global_load_lds_dwordx4 v[92:93], off
	s_add_u32 m0, m0, 0x1000
	v_lshl_add_u64 v[92:93], v[92:93], 0, s[40:41]
	global_load_lds_dwordx4 v[92:93], off
	s_add_u32 m0, m0, 0x1000
	s_nop 0
	global_load_lds_dwordx4 v[90:91], off
	s_add_u32 m0, m0, 0x1000
	v_lshl_add_u64 v[90:91], v[90:91], 0, s[40:41]
	global_load_lds_dwordx4 v[90:91], off
	s_add_u32 m0, m0, 0x1000
	v_lshl_add_u64 v[90:91], v[90:91], 0, s[40:41]
	global_load_lds_dwordx4 v[90:91], off
	s_add_u32 m0, m0, 0x1000
	v_lshl_add_u64 v[90:91], v[90:91], 0, s[40:41]
	global_load_lds_dwordx4 v[90:91], off
	s_branch .LBB0_131
